# baseline (speedup 1.0000x reference)
; __device__ __forceinline__ float bf2f(bf16_t v) { return __uint_as_float((unsigned)v << 16); }
; __device__ __forceinline__ float fast_exp2(float x) { return __builtin_amdgcn_exp2f(x); }
; template <bool FIXED> ...
;     ...
;     {
;         const bf16_t* Qw = Qb + (size_t)(wid * QBLK + r32) * LDQ + hi * 8;
;         bf16x8 raw[8];
; #pragma unroll
;         for (int d0 = 0; d0 < 8; ++d0) raw[d0] = *reinterpret_cast<const bf16x8*>(Qw + d0 * 16);
;         float ss = 0.f;
; #pragma unroll
;         for (int d0 = 0; d0 < 8; ++d0)
; #pragma unroll
;             for (int e = 0; e < 8; ++e) { const float f = bf2f((bf16_t)raw[d0][e]); ss += f * f; }
;         { auto rr = __builtin_amdgcn_permlane32_swap(__float_as_uint(ss), __float_as_uint(ss), false, false); ss = __uint_as_float(rr[0]) + __uint_as_float(rr[1]); }
;         const float rinv = rsqrtf(ss * (1.f / 128.f) + 1e-6f) * (FIXED ? SCALE * 1.4426950408889634f * 8.f : 1.f);
;         const int t = pos0 + wid * QBLK + r32; const float prow = (float)(t >> 6), pcol = (float)(t & 63);
; #pragma unroll
;         for (int pr = 0; pr < 4; ++pr) { const int da = (pr & 1) + ((pr >> 1) << 2), db = da + 2; const float pos = (pr >> 1) ? pcol : prow; float oa[8], ob[8];
; #pragma unroll
;             for (int e = 0; e < 8; ++e) { const int i = (da & 1) * 16 + hi * 8 + e; const float rev = pos * fast_exp2(-(float)i * ROPE_L2) * INV2PI;
;                 const float cs = __builtin_amdgcn_cosf(rev), sn = __builtin_amdgcn_sinf(rev);
;                 const float fa = bf2f((bf16_t)raw[da][e]) * rinv * qg[da * 16 + hi * 8 + e], fb = bf2f((bf16_t)raw[db][e]) * rinv * qg[db * 16 + hi * 8 + e];
;                 oa[e] = fa * cs - fb * sn; ob[e] = fb * cs + fa * sn; }
.LBB0_1026:
	s_mul_i32 s20, s67, 0x4800
	s_mul_hi_u32 s40, s67, 0x4800
	s_add_u32 s20, s18, s20
	s_addc_u32 s68, s19, s40
	s_lshl_b32 s40, s35, 7
	s_ashr_i32 s41, s40, 31
	s_lshl_b64 s[42:43], s[40:41], 1
	s_add_u32 s48, s20, s42
	v_mov_b32_e32 v195, v177
	s_barrier
	s_addc_u32 s49, s68, s43
	v_mov_b64_e32 v[0:1], s[48:49]
	v_ashrrev_i32_e32 v8, 1, v195
	v_bfe_u32 v114, v195, 5, 1
	v_bfi_b32 v2, s54, v8, v195
	v_readlane_b32 s72, v254, 19
	v_mad_i64_i32 v[0:1], s[48:49], v2, s33, v[0:1]
	v_lshlrev_b32_e32 v178, 4, v114
	v_and_b32_e32 v193, 32, v195
	v_readlane_b32 s82, v254, 29
	v_readlane_b32 s83, v254, 30
	v_lshl_add_u64 v[12:13], v[0:1], 0, v[178:179]
	s_nop 3
	global_load_dwordx4 v[24:27], v193, s[82:83]
	global_load_dwordx4 v[4:7], v193, s[82:83] offset:128
	global_load_dwordx4 v[28:31], v[12:13], off offset:64
	global_load_dwordx4 v[32:35], v[12:13], off
	global_load_dwordx4 v[36:39], v193, s[82:83] offset:16
	global_load_dwordx4 v[0:3], v193, s[82:83] offset:144
	global_load_dwordx4 v[208:211], v193, s[82:83] offset:80
	global_load_dwordx4 v[212:215], v193, s[82:83] offset:64
	global_load_dwordx4 v[216:219], v193, s[82:83] offset:192
	global_load_dwordx4 v[220:223], v193, s[82:83] offset:208
	global_load_dwordx4 v[224:227], v193, s[82:83] offset:256
	global_load_dwordx4 v[228:231], v193, s[82:83] offset:384
	global_load_dwordx4 v[232:235], v193, s[82:83] offset:272
	global_load_dwordx4 v[236:239], v193, s[82:83] offset:400
	global_load_dwordx4 v[240:243], v193, s[82:83] offset:320
	global_load_dwordx4 v[244:247], v193, s[82:83] offset:448
	global_load_dwordx4 v[248:251], v193, s[82:83] offset:336
	global_load_dwordx4 v[184:187], v193, s[82:83] offset:464
	v_and_b32_e32 v192, 31, v195
	v_and_b32_e32 v191, 0xffffffe0, v8
	v_lshlrev_b32_e32 v123, 3, v114
	v_or_b32_e32 v8, s3, v192
	v_add_u32_e32 v115, v8, v191
	v_cvt_f32_ubyte0_e32 v8, v123
	v_or_b32_e32 v9, 1, v123
	v_or_b32_e32 v10, 2, v123
	v_or_b32_e32 v11, 3, v123
	v_or_b32_e32 v14, 4, v123
	v_mul_f32_e32 v8, 0xbed49a78, v8
	v_cvt_f32_ubyte0_e32 v9, v9
	v_cvt_f32_ubyte0_e32 v10, v10
	v_cvt_f32_ubyte0_e32 v11, v11
	v_cvt_f32_ubyte0_e32 v14, v14
	v_ashrrev_i32_e32 v15, 6, v115
	v_exp_f32_e32 v119, v8
	v_mul_f32_e32 v8, 0xbed49a78, v9
	v_mul_f32_e32 v9, 0xbed49a78, v10
	v_mul_f32_e32 v10, 0xbed49a78, v11
	v_mul_f32_e32 v11, 0xbed49a78, v14
	v_cvt_f32_i32_e32 v125, v15
	v_exp_f32_e32 v120, v8
	v_exp_f32_e32 v118, v9
	v_exp_f32_e32 v117, v10
	v_exp_f32_e32 v116, v11
	global_load_dwordx4 v[46:49], v[12:13], off offset:32
	global_load_dwordx4 v[126:129], v[12:13], off offset:96
	global_load_dwordx4 v[16:19], v[12:13], off offset:128
	global_load_dwordx4 v[8:11], v[12:13], off offset:160
	global_load_dwordx4 v[20:23], v[12:13], off offset:192
	s_nop 0
	global_load_dwordx4 v[12:15], v[12:13], off offset:224
	v_mul_f32_e32 v40, v119, v125
	v_mul_f32_e32 v40, 0.15915494, v40
	v_mul_f32_e32 v41, v120, v125
	v_mul_f32_e32 v42, v118, v125
	v_cos_f32_e32 v58, v40
	v_sin_f32_e32 v59, v40
	v_mul_f32_e32 v40, 0.15915494, v41
	v_mul_f32_e32 v41, 0.15915494, v42
	v_cos_f32_e32 v54, v40
	v_sin_f32_e32 v55, v40
	v_cos_f32_e32 v50, v41
	v_sin_f32_e32 v51, v41
	v_or_b32_e32 v133, 16, v123
	v_mov_b32_e32 v112, v59
	v_mov_b32_e32 v113, v58
	v_mul_f32_e32 v43, v117, v125
	v_mov_b32_e32 v110, v55
	v_mov_b32_e32 v111, v54
	v_mul_f32_e32 v43, 0.15915494, v43
	v_cos_f32_e32 v42, v43
	v_sin_f32_e32 v43, v43
	v_mov_b32_e32 v108, v51
	v_mov_b32_e32 v109, v50
	v_mov_b32_e32 v107, v42
	v_mov_b32_e32 v106, v43
	s_lshl_b32 s50, s44, 7
	s_lshl_b64 s[48:49], s[46:47], 9
	s_ashr_i32 s51, s50, 31
	s_add_u32 s3, s38, s48
	s_addc_u32 s35, s39, s49
	s_add_u32 s52, s3, s50
	s_addc_u32 s53, s35, s51
	s_lshr_b32 s3, s46, 4
	s_and_b32 s3, s3, 0x7fffffc
	s_ashr_i32 s45, s44, 31
	s_add_u32 s46, s3, s44
	s_addc_u32 s47, 0, s45
	s_lshl_b64 s[46:47], s[46:47], 13
	s_add_u32 s46, s36, s46
	s_addc_u32 s47, s37, s47
	v_lshlrev_b32_e32 v252, 4, v195
	v_lshrrev_b32_e32 v253, 3, v195
	global_load_dwordx4 v[136:139], v252, s[46:47]
	v_and_b32_e32 v135, 0x70, v252
	v_lshl_or_b32 v253, v253, 9, v135
	v_add_u32_e32 v252, 0x8000, v252
	global_load_dwordx4 v[140:143], v253, s[52:53]
	v_add_u32_e32 v253, 0x8000, v253
	global_load_dwordx4 v[168:171], v252, s[46:47]
	global_load_dwordx4 v[172:175], v253, s[52:53]
	v_mov_b32_e32 v153, v179
	v_mov_b32_e32 v157, v179
	v_mov_b32_e32 v156, v179
	v_mov_b32_e32 v146, v179
	v_mov_b32_e32 v147, v179
	v_mov_b32_e32 v150, v179
	v_lshlrev_b32_e32 v201, 7, v192
	v_mov_b32_e32 v151, v179
	v_add_u32_e32 v204, 0, v201
	s_waitcnt vmcnt(9)
	v_lshlrev_b32_e32 v81, 16, v28
	v_and_b32_e32 v79, 0xffff0000, v28
	v_mul_f32_e32 v28, v116, v125
	v_mul_f32_e32 v28, 0.15915494, v28
	v_cos_f32_e32 v66, v28
	v_sin_f32_e32 v67, v28
	v_or_b32_e32 v28, 5, v123
	v_cvt_f32_ubyte0_e32 v28, v28
	v_mul_f32_e32 v28, 0xbed49a78, v28
	v_exp_f32_e32 v121, v28
	s_waitcnt vmcnt(6)
	v_mov_b32_e32 v85, v0
	v_and_b32_e32 v78, 0xffff0000, v32
	v_mov_b32_e32 v74, v24
	v_mul_f32_e32 v0, v121, v125
	v_mul_f32_e32 v0, 0.15915494, v0
	v_cos_f32_e32 v82, v0
	v_sin_f32_e32 v83, v0
	v_or_b32_e32 v0, 6, v123
	v_cvt_f32_ubyte0_e32 v0, v0
	v_mul_f32_e32 v0, 0xbed49a78, v0
	v_exp_f32_e32 v122, v0
	v_mov_b32_e32 v75, v4
	v_mov_b32_e32 v4, v25
	v_lshlrev_b32_e32 v80, 16, v32
	v_mul_f32_e32 v28, v122, v125
	v_pk_mul_f32 v[24:25], v[78:79], v[78:79]
	v_mul_f32_e32 v28, 0.15915494, v28
	v_mov_b32_e32 v62, v26
	v_mov_b32_e32 v63, v6
	v_mov_b32_e32 v6, v27
	v_lshlrev_b32_e32 v73, 16, v29
	v_lshlrev_b32_e32 v72, 16, v33
	v_pk_fma_f32 v[26:27], v[80:81], v[80:81], v[24:25]
	v_cos_f32_e32 v88, v28
	v_sin_f32_e32 v89, v28
	v_or_b32_e32 v28, 7, v123
	v_and_b32_e32 v69, 0xffff0000, v29
	v_and_b32_e32 v68, 0xffff0000, v33
	v_pk_fma_f32 v[26:27], v[72:73], v[72:73], v[26:27]
	v_cvt_f32_ubyte0_e32 v28, v28
	v_pk_fma_f32 v[26:27], v[68:69], v[68:69], v[26:27]
	v_lshlrev_b32_e32 v71, 16, v30
	v_lshlrev_b32_e32 v70, 16, v34
	v_mul_f32_e32 v28, 0xbed49a78, v28
	v_pk_fma_f32 v[26:27], v[70:71], v[70:71], v[26:27]
	v_and_b32_e32 v87, 0xffff0000, v30
	v_and_b32_e32 v86, 0xffff0000, v34
	v_exp_f32_e32 v124, v28
	v_pk_fma_f32 v[26:27], v[86:87], v[86:87], v[26:27]
	v_lshlrev_b32_e32 v91, 16, v31
	v_lshlrev_b32_e32 v90, 16, v35
	v_pk_fma_f32 v[26:27], v[90:91], v[90:91], v[26:27]
	v_and_b32_e32 v97, 0xffff0000, v31
	v_and_b32_e32 v96, 0xffff0000, v35
	v_pk_fma_f32 v[28:29], v[96:97], v[96:97], v[26:27]
	s_waitcnt vmcnt(4)
; __device__ __forceinline__ float bf2f(bf16_t v) { return __uint_as_float((unsigned)v << 16); }
; template <bool FIXED> ...
;     ...
;         float ss = 0.f;
; #pragma unroll
;         for (int d0 = 0; d0 < 8; ++d0)
; #pragma unroll
;             for (int e = 0; e < 8; ++e) { const float f = bf2f((bf16_t)raw[d0][e]); ss += f * f; }
;         { auto rr = __builtin_amdgcn_permlane32_swap(__float_as_uint(ss), __float_as_uint(ss), false, false); ss = __uint_as_float(rr[0]) + __uint_as_float(rr[1]); }
	v_lshlrev_b32_e32 v27, 16, v126
	v_lshlrev_b32_e32 v26, 16, v46
	v_mov_b32_e32 v95, v2
	v_mul_f32_e32 v2, v124, v125
	v_pk_fma_f32 v[30:31], v[26:27], v[26:27], v[28:29]
	v_and_b32_e32 v29, 0xffff0000, v126
	v_and_b32_e32 v28, 0xffff0000, v46
	v_mul_f32_e32 v2, 0.15915494, v2
	v_pk_fma_f32 v[32:33], v[28:29], v[28:29], v[30:31]
	v_lshlrev_b32_e32 v31, 16, v127
	v_lshlrev_b32_e32 v30, 16, v47
	v_mov_b32_e32 v94, v38
	v_cos_f32_e32 v92, v2
	v_sin_f32_e32 v93, v2
	v_mov_b32_e32 v2, v39
	v_pk_fma_f32 v[32:33], v[30:31], v[30:31], v[32:33]
	v_and_b32_e32 v39, 0xffff0000, v127
	v_and_b32_e32 v38, 0xffff0000, v47
	v_pk_fma_f32 v[32:33], v[38:39], v[38:39], v[32:33]
	v_lshlrev_b32_e32 v47, 16, v128
	v_lshlrev_b32_e32 v46, 16, v48
	v_pk_fma_f32 v[32:33], v[46:47], v[46:47], v[32:33]
	v_and_b32_e32 v57, 0xffff0000, v128
	v_and_b32_e32 v56, 0xffff0000, v48
	v_pk_fma_f32 v[32:33], v[56:57], v[56:57], v[32:33]
	v_lshlrev_b32_e32 v65, 16, v129
	v_lshlrev_b32_e32 v64, 16, v49
	v_pk_fma_f32 v[32:33], v[64:65], v[64:65], v[32:33]
	v_and_b32_e32 v77, 0xffff0000, v129
	v_and_b32_e32 v76, 0xffff0000, v49
	v_pk_fma_f32 v[32:33], v[76:77], v[76:77], v[32:33]
	v_mul_f32_e32 v34, v81, v81
	v_pk_add_f32 v[32:33], v[34:35], v[32:33] op_sel_hi:[0,1]
	v_pk_add_f32 v[24:25], v[24:25], v[32:33] op_sel:[1,0] op_sel_hi:[0,1]
	v_mul_f32_e32 v32, v73, v73
	v_pk_add_f32 v[24:25], v[32:33], v[24:25] op_sel_hi:[0,1]
	v_mul_f32_e32 v32, v69, v69
	v_pk_add_f32 v[24:25], v[32:33], v[24:25] op_sel_hi:[0,1]
	v_mul_f32_e32 v32, v71, v71
	v_pk_add_f32 v[24:25], v[32:33], v[24:25] op_sel_hi:[0,1]
	v_mul_f32_e32 v32, v87, v87
	v_pk_add_f32 v[24:25], v[32:33], v[24:25] op_sel_hi:[0,1]
	v_mul_f32_e32 v32, v91, v91
	v_pk_add_f32 v[24:25], v[32:33], v[24:25] op_sel_hi:[0,1]
	v_mul_f32_e32 v32, v97, v97
	v_pk_add_f32 v[24:25], v[32:33], v[24:25] op_sel_hi:[0,1]
	v_mul_f32_e32 v32, v27, v27
	v_pk_add_f32 v[24:25], v[32:33], v[24:25] op_sel_hi:[0,1]
	v_mul_f32_e32 v32, v29, v29
	v_pk_add_f32 v[24:25], v[32:33], v[24:25] op_sel_hi:[0,1]
	v_mul_f32_e32 v32, v31, v31
	v_pk_add_f32 v[24:25], v[32:33], v[24:25] op_sel_hi:[0,1]
	v_mul_f32_e32 v32, v39, v39
	v_pk_add_f32 v[24:25], v[32:33], v[24:25] op_sel_hi:[0,1]
	v_mul_f32_e32 v32, v47, v47
	v_pk_add_f32 v[24:25], v[32:33], v[24:25] op_sel_hi:[0,1]
	v_mul_f32_e32 v32, v57, v57
	v_pk_add_f32 v[24:25], v[32:33], v[24:25] op_sel_hi:[0,1]
	v_mul_f32_e32 v32, v65, v65
	v_pk_add_f32 v[24:25], v[32:33], v[24:25] op_sel_hi:[0,1]
	v_mul_f32_e32 v32, v77, v77
	v_pk_add_f32 v[24:25], v[32:33], v[24:25] op_sel_hi:[0,1]
	s_waitcnt vmcnt(1)
	v_lshlrev_b32_e32 v33, 16, v20
	v_lshlrev_b32_e32 v32, 16, v16
	v_pk_fma_f32 v[24:25], v[32:33], v[32:33], v[24:25]
	v_and_b32_e32 v35, 0xffff0000, v20
	v_and_b32_e32 v34, 0xffff0000, v16
	v_mov_b32_e32 v84, v36
	v_mov_b32_e32 v0, v37
	v_pk_fma_f32 v[24:25], v[34:35], v[34:35], v[24:25]
	v_lshlrev_b32_e32 v37, 16, v21
	v_lshlrev_b32_e32 v36, 16, v17
	v_pk_fma_f32 v[24:25], v[36:37], v[36:37], v[24:25]
	v_and_b32_e32 v41, 0xffff0000, v21
	v_and_b32_e32 v40, 0xffff0000, v17
	v_pk_fma_f32 v[16:17], v[40:41], v[40:41], v[24:25]
	v_lshlrev_b32_e32 v45, 16, v22
	v_lshlrev_b32_e32 v44, 16, v18
	v_pk_fma_f32 v[16:17], v[44:45], v[44:45], v[16:17]
	v_and_b32_e32 v49, 0xffff0000, v22
	v_and_b32_e32 v48, 0xffff0000, v18
	v_pk_fma_f32 v[16:17], v[48:49], v[48:49], v[16:17]
	v_lshlrev_b32_e32 v53, 16, v23
	v_lshlrev_b32_e32 v52, 16, v19
	v_pk_fma_f32 v[16:17], v[52:53], v[52:53], v[16:17]
	v_and_b32_e32 v61, 0xffff0000, v23
	v_and_b32_e32 v60, 0xffff0000, v19
	v_pk_fma_f32 v[16:17], v[60:61], v[60:61], v[16:17]
	s_waitcnt vmcnt(0)
	v_lshlrev_b32_e32 v21, 16, v12
	v_lshlrev_b32_e32 v20, 16, v8
	v_pk_fma_f32 v[18:19], v[20:21], v[20:21], v[16:17]
	v_and_b32_e32 v17, 0xffff0000, v12
	v_and_b32_e32 v16, 0xffff0000, v8
	v_pk_fma_f32 v[22:23], v[16:17], v[16:17], v[18:19]
	v_lshlrev_b32_e32 v19, 16, v13
	v_lshlrev_b32_e32 v18, 16, v9
	v_pk_fma_f32 v[22:23], v[18:19], v[18:19], v[22:23]
	v_and_b32_e32 v13, 0xffff0000, v13
	v_and_b32_e32 v12, 0xffff0000, v9
	v_pk_fma_f32 v[22:23], v[12:13], v[12:13], v[22:23]
	v_lshlrev_b32_e32 v9, 16, v14
	v_lshlrev_b32_e32 v8, 16, v10
	v_pk_fma_f32 v[24:25], v[8:9], v[8:9], v[22:23]
	v_and_b32_e32 v23, 0xffff0000, v14
	v_and_b32_e32 v22, 0xffff0000, v10
	v_pk_fma_f32 v[130:131], v[22:23], v[22:23], v[24:25]
	v_lshlrev_b32_e32 v25, 16, v15
	v_lshlrev_b32_e32 v24, 16, v11
	v_pk_fma_f32 v[130:131], v[24:25], v[24:25], v[130:131]
	v_and_b32_e32 v15, 0xffff0000, v15
	v_and_b32_e32 v14, 0xffff0000, v11
	v_pk_fma_f32 v[130:131], v[14:15], v[14:15], v[130:131]
	v_mul_f32_e32 v132, v33, v33
	v_pk_add_f32 v[130:131], v[132:133], v[130:131] op_sel_hi:[0,1]
	v_mul_f32_e32 v132, v35, v35
	v_pk_add_f32 v[130:131], v[132:133], v[130:131] op_sel_hi:[0,1]
	v_mul_f32_e32 v132, v37, v37
	v_pk_add_f32 v[130:131], v[132:133], v[130:131] op_sel_hi:[0,1]
	v_mul_f32_e32 v132, v41, v41
	v_pk_add_f32 v[130:131], v[132:133], v[130:131] op_sel_hi:[0,1]
	v_mul_f32_e32 v132, v45, v45
	v_pk_add_f32 v[130:131], v[132:133], v[130:131] op_sel_hi:[0,1]
	v_mul_f32_e32 v132, v49, v49
	v_pk_add_f32 v[130:131], v[132:133], v[130:131] op_sel_hi:[0,1]
	v_mul_f32_e32 v132, v53, v53
	v_pk_add_f32 v[130:131], v[132:133], v[130:131] op_sel_hi:[0,1]
	v_mul_f32_e32 v132, v61, v61
	v_pk_add_f32 v[130:131], v[132:133], v[130:131] op_sel_hi:[0,1]
	v_mul_f32_e32 v132, v21, v21
	v_pk_add_f32 v[130:131], v[132:133], v[130:131] op_sel_hi:[0,1]
	v_mul_f32_e32 v132, v17, v17
	v_pk_add_f32 v[130:131], v[132:133], v[130:131] op_sel_hi:[0,1]
	v_mul_f32_e32 v132, v19, v19
	v_mov_b32_e32 v126, v13
	v_mov_b32_e32 v127, v19
	v_pk_add_f32 v[130:131], v[132:133], v[130:131] op_sel_hi:[0,1]
; __device__ __forceinline__ unsigned cvt_pk_bf16(float lo, float hi) { unsigned r; asm volatile("v_cvt_pk_bf16_f32 %0, %1, %2" : "=v"(r) : "v"(lo), "v"(hi)); return r; }
; __device__ __forceinline__ float bf2f(bf16_t v) { return __uint_as_float((unsigned)v << 16); }
; __device__ __forceinline__ float fast_exp2(float x) { return __builtin_amdgcn_exp2f(x); }
; template <bool FIXED> ...
;     ...
;         { auto rr = __builtin_amdgcn_permlane32_swap(__float_as_uint(ss), __float_as_uint(ss), false, false); ss = __uint_as_float(rr[0]) + __uint_as_float(rr[1]); }
;         const float rinv = rsqrtf(ss * (1.f / 128.f) + 1e-6f) * (FIXED ? SCALE * 1.4426950408889634f * 8.f : 1.f);
;         const int t = pos0 + wid * QBLK + r32; const float prow = (float)(t >> 6), pcol = (float)(t & 63);
; #pragma unroll
;         for (int pr = 0; pr < 4; ++pr) { const int da = (pr & 1) + ((pr >> 1) << 2), db = da + 2; const float pos = (pr >> 1) ? pcol : prow; float oa[8], ob[8];
; #pragma unroll
;             for (int e = 0; e < 8; ++e) { const int i = (da & 1) * 16 + hi * 8 + e; const float rev = pos * fast_exp2(-(float)i * ROPE_L2) * INV2PI;
;                 const float cs = __builtin_amdgcn_cosf(rev), sn = __builtin_amdgcn_sinf(rev);
;                 const float fa = bf2f((bf16_t)raw[da][e]) * rinv * qg[da * 16 + hi * 8 + e], fb = bf2f((bf16_t)raw[db][e]) * rinv * qg[db * 16 + hi * 8 + e];
;                 oa[e] = fa * cs - fb * sn; ob[e] = fb * cs + fa * sn; }
;             u32x4 wa = {cvt_pk_bf16(oa[0], oa[1]), cvt_pk_bf16(oa[2], oa[3]), cvt_pk_bf16(oa[4], oa[5]), cvt_pk_bf16(oa[6], oa[7])};
;             u32x4 wb = {cvt_pk_bf16(ob[0], ob[1]), cvt_pk_bf16(ob[2], ob[3]), cvt_pk_bf16(ob[4], ob[5]), cvt_pk_bf16(ob[6], ob[7])};
;             if constexpr (FIXED) { const u32x2 fa = pack8_fp8((f32x4){oa[0], oa[1], oa[2], oa[3]}, (f32x4){oa[4], oa[5], oa[6], oa[7]}), fb = pack8_fp8((f32x4){ob[0], ob[1], ob[2], ob[3]}, (f32x4){ob[4], ob[5], ob[6], ob[7]});
;                 q8[da >> 2][2 * (da & 3)] = (int)fa.x; q8[da >> 2][2 * (da & 3) + 1] = (int)fa.y; q8[db >> 2][2 * (db & 3)] = (int)fb.x; q8[db >> 2][2 * (db & 3) + 1] = (int)fb.y; }
;             else { qr[da] = *reinterpret_cast<bf16x8*>(&wa); qr[db] = *reinterpret_cast<bf16x8*>(&wb); }
;             asm volatile("" ::: "memory"); }
	v_pk_fma_f32 v[126:127], v[126:127], v[126:127], v[130:131]
	v_mul_f32_e32 v130, v9, v9
	v_mov_b32_e32 v128, v23
	v_mov_b32_e32 v129, v9
	v_pk_add_f32 v[126:127], v[130:131], v[126:127] op_sel_hi:[0,1]
	v_pk_fma_f32 v[126:127], v[128:129], v[128:129], v[126:127]
	v_mul_f32_e32 v128, v25, v25
	v_mov_b32_e32 v10, v15
	v_mov_b32_e32 v11, v25
	v_pk_add_f32 v[126:127], v[128:129], v[126:127] op_sel_hi:[0,1]
	v_pk_fma_f32 v[10:11], v[10:11], v[10:11], v[126:127]
	v_mov_b32_e32 v104, v67
	v_mov_b32_e32 v11, v10
	s_nop 1
	v_permlane32_swap_b32_e32 v10, v11
	v_add_f32_e32 v10, v10, v11
	v_fmamk_f32 v10, v10, 0x3c000000, v188
	v_mul_f32_e32 v11, 0x4b800000, v10
	v_cmp_gt_f32_e32 vcc, s55, v10
	v_mov_b32_e32 v105, v66
	v_mov_b32_e32 v102, v83
	v_cndmask_b32_e32 v10, v10, v11, vcc
	v_rsq_f32_e32 v10, v10
	v_cvt_f32_ubyte0_e32 v11, v133
	v_mul_f32_e32 v11, 0xbed49a78, v11
	v_exp_f32_e32 v128, v11
	v_mul_f32_e32 v11, 0x45800000, v10
	v_cndmask_b32_e32 v10, v10, v11, vcc
	v_mul_f32_e32 v10, 0x3f8293ee, v10
	v_pk_mul_f32 v[80:81], v[10:11], v[80:81] op_sel_hi:[0,1]
	v_pk_mul_f32 v[74:75], v[74:75], v[80:81]
	v_mov_b32_e32 v103, v82
	v_pk_mul_f32 v[58:59], v[58:59], v[74:75]
	v_pk_mul_f32 v[74:75], v[112:113], v[74:75]
	v_mov_b32_e32 v100, v89
	v_add_f32_e32 v11, v74, v75
	v_pk_mul_f32 v[74:75], v[10:11], v[78:79] op_sel_hi:[0,1]
	v_pk_mul_f32 v[74:75], v[4:5], v[74:75]
	v_mov_b32_e32 v101, v88
	v_pk_mul_f32 v[4:5], v[54:55], v[74:75]
	v_pk_mul_f32 v[54:55], v[110:111], v[74:75]
	v_sub_f32_e32 v5, v4, v5
	v_add_f32_e32 v4, v54, v55
	v_pk_mul_f32 v[54:55], v[10:11], v[72:73] op_sel_hi:[0,1]
	v_pk_mul_f32 v[54:55], v[62:63], v[54:55]
	v_pk_mul_f32 v[62:63], v[10:11], v[90:91] op_sel_hi:[0,1]
	v_pk_mul_f32 v[50:51], v[50:51], v[54:55]
	v_pk_mul_f32 v[54:55], v[108:109], v[54:55]
	v_sub_f32_e32 v50, v50, v51
	v_add_f32_e32 v51, v54, v55
	v_pk_mul_f32 v[54:55], v[10:11], v[68:69] op_sel_hi:[0,1]
	v_pk_mul_f32 v[54:55], v[6:7], v[54:55]
	v_pk_mul_f32 v[62:63], v[62:63], v[94:95]
	v_pk_mul_f32 v[6:7], v[42:43], v[54:55]
	v_pk_mul_f32 v[42:43], v[106:107], v[54:55]
	v_sub_f32_e32 v6, v6, v7
	v_add_f32_e32 v7, v42, v43
	v_pk_mul_f32 v[42:43], v[10:11], v[70:71] op_sel_hi:[0,1]
	v_pk_mul_f32 v[54:55], v[84:85], v[42:43]
	v_mov_b32_e32 v98, v93
	v_pk_mul_f32 v[42:43], v[66:67], v[54:55]
	v_pk_mul_f32 v[54:55], v[104:105], v[54:55]
	v_sub_f32_e32 v43, v42, v43
	v_add_f32_e32 v42, v54, v55
	v_pk_mul_f32 v[54:55], v[10:11], v[86:87] op_sel_hi:[0,1]
	v_pk_mul_f32 v[0:1], v[0:1], v[54:55]
	v_pk_mul_f32 v[66:67], v[88:89], v[62:63]
	v_pk_mul_f32 v[54:55], v[82:83], v[0:1]
	v_pk_mul_f32 v[0:1], v[102:103], v[0:1]
	v_pk_mul_f32 v[62:63], v[100:101], v[62:63]
	v_add_f32_e32 v1, v0, v1
	v_add_f32_e32 v0, v62, v63
	v_pk_mul_f32 v[62:63], v[10:11], v[96:97] op_sel_hi:[0,1]
	v_mov_b32_e32 v99, v92
	v_pk_mul_f32 v[62:63], v[62:63], v[2:3]
	v_sub_f32_e32 v58, v58, v59
	v_pk_mul_f32 v[2:3], v[92:93], v[62:63]
	v_pk_mul_f32 v[62:63], v[98:99], v[62:63]
	v_sub_f32_e32 v54, v54, v55
	v_sub_f32_e32 v55, v66, v67
	v_sub_f32_e32 v3, v2, v3
	v_add_f32_e32 v2, v62, v63
	v_cvt_pk_bf16_f32 v59, v58, v5
	v_or_b32_e32 v62, 17, v123
	v_cvt_pk_bf16_f32 v59, v50, v6
	v_cvt_f32_ubyte0_e32 v62, v62
	v_cvt_pk_bf16_f32 v59, v43, v54
	v_mul_f32_e32 v62, 0xbed49a78, v62
	v_cvt_pk_bf16_f32 v59, v55, v3
	v_or_b32_e32 v74, 18, v123
	v_cvt_pk_bf16_f32 v59, v11, v4
	v_exp_f32_e32 v129, v62
	v_cvt_pk_bf16_f32 v59, v51, v7
	v_cvt_f32_ubyte0_e32 v74, v74
	v_cvt_pk_bf16_f32 v59, v42, v1
	v_mul_f32_e32 v74, 0xbed49a78, v74
	v_cvt_pk_bf16_f32 v59, v0, v2
	v_mov_b64_e32 v[66:67], v[208:209]
	v_mov_b64_e32 v[68:69], v[210:211]
	v_mov_b64_e32 v[70:71], v[212:213]
	v_mov_b64_e32 v[72:73], v[214:215]
	v_mov_b64_e32 v[78:79], v[216:217]
	v_mov_b64_e32 v[80:81], v[218:219]
	v_mov_b64_e32 v[82:83], v[220:221]
	v_mov_b64_e32 v[84:85], v[222:223]
	v_or_b32_e32 v86, 19, v123
	v_mul_f32_e32 v59, v128, v125
	v_exp_f32_e32 v130, v74
	v_cvt_f32_ubyte0_e32 v86, v86
	v_mul_f32_e32 v59, 0.15915494, v59
	v_mul_f32_e32 v86, 0xbed49a78, v86
	v_or_b32_e32 v88, 20, v123
	v_cos_f32_e32 v62, v59
	v_sin_f32_e32 v63, v59
	v_mul_f32_e32 v59, v129, v125
	v_exp_f32_e32 v131, v86
	v_cvt_f32_ubyte0_e32 v88, v88
	v_mul_f32_e32 v59, 0.15915494, v59
	v_mul_f32_e32 v88, 0xbed49a78, v88
	v_or_b32_e32 v90, 21, v123
	v_cos_f32_e32 v74, v59
	v_sin_f32_e32 v75, v59
	v_mul_f32_e32 v59, v130, v125
	v_exp_f32_e32 v132, v88
	v_cvt_f32_ubyte0_e32 v90, v90
	v_mul_f32_e32 v59, 0.15915494, v59
	v_mul_f32_e32 v90, 0xbed49a78, v90
	v_or_b32_e32 v92, 22, v123
	v_cos_f32_e32 v86, v59
	v_sin_f32_e32 v87, v59
	v_mul_f32_e32 v59, v131, v125
	v_exp_f32_e32 v133, v90
	v_cvt_f32_ubyte0_e32 v92, v92
	v_mul_f32_e32 v59, 0.15915494, v59
	v_mul_f32_e32 v92, 0xbed49a78, v92
	v_or_b32_e32 v94, 23, v123
	v_cos_f32_e32 v88, v59
	v_sin_f32_e32 v89, v59
	v_mul_f32_e32 v59, v132, v125
	v_exp_f32_e32 v134, v92
	v_cvt_f32_ubyte0_e32 v94, v94
	v_mul_f32_e32 v59, 0.15915494, v59
	v_mul_f32_e32 v94, 0xbed49a78, v94
	v_cos_f32_e32 v90, v59
	v_sin_f32_e32 v91, v59
	v_mul_f32_e32 v59, v133, v125
	v_exp_f32_e32 v123, v94
	v_mul_f32_e32 v59, 0.15915494, v59
	v_pk_mul_f32 v[26:27], v[10:11], v[26:27] op_sel_hi:[0,1]
	v_cos_f32_e32 v92, v59
	v_sin_f32_e32 v93, v59
	v_mul_f32_e32 v59, v134, v125
	v_mov_b32_e32 v98, v63
	v_mov_b32_e32 v99, v62
	v_mul_f32_e32 v59, 0.15915494, v59
	v_cos_f32_e32 v94, v59
	v_sin_f32_e32 v95, v59
	v_mul_f32_e32 v59, v123, v125
	v_mov_b32_e32 v100, v75
	v_mov_b32_e32 v101, v74
	v_mov_b32_e32 v102, v87
	v_mov_b32_e32 v103, v86
	v_mov_b32_e32 v104, v89
	v_mov_b32_e32 v105, v88
	v_mov_b32_e32 v106, v91
	v_mov_b32_e32 v107, v90
	v_mov_b32_e32 v108, v93
	v_mov_b32_e32 v109, v92
	v_mul_f32_e32 v59, 0.15915494, v59
	v_cos_f32_e32 v96, v59
	v_sin_f32_e32 v97, v59
	v_mov_b32_e32 v110, v95
	v_mov_b32_e32 v111, v94
	v_mov_b32_e32 v113, v96
	v_mov_b32_e32 v112, v97
	v_pk_mul_f32 v[32:33], v[10:11], v[32:33] op_sel_hi:[0,1]
	v_pk_mul_f32 v[20:21], v[10:11], v[20:21] op_sel_hi:[0,1]
	v_pk_mul_f32 v[16:17], v[10:11], v[16:17] op_sel_hi:[0,1]
	v_pk_mul_f32 v[12:13], v[10:11], v[12:13] op_sel_hi:[0,1]
	v_pk_mul_f32 v[8:9], v[10:11], v[8:9] op_sel_hi:[0,1]
	v_cvt_pk_fp8_f32 v153, v43, v54
	v_cvt_pk_fp8_f32 v157, v42, v1
	s_waitcnt vmcnt(2)
; __device__ __forceinline__ unsigned cvt_pk_bf16(float lo, float hi) { unsigned r; asm volatile("v_cvt_pk_bf16_f32 %0, %1, %2" : "=v"(r) : "v"(lo), "v"(hi)); return r; }
; __device__ __forceinline__ float bf2f(bf16_t v) { return __uint_as_float((unsigned)v << 16); }
; __device__ __forceinline__ float fast_exp2(float x) { return __builtin_amdgcn_exp2f(x); }
; template <bool FIXED> ...
;     ...
;         for (int pr = 0; pr < 4; ++pr) { const int da = (pr & 1) + ((pr >> 1) << 2), db = da + 2; const float pos = (pr >> 1) ? pcol : prow; float oa[8], ob[8];
; #pragma unroll
;             for (int e = 0; e < 8; ++e) { const int i = (da & 1) * 16 + hi * 8 + e; const float rev = pos * fast_exp2(-(float)i * ROPE_L2) * INV2PI;
;                 const float cs = __builtin_amdgcn_cosf(rev), sn = __builtin_amdgcn_sinf(rev);
;                 const float fa = bf2f((bf16_t)raw[da][e]) * rinv * qg[da * 16 + hi * 8 + e], fb = bf2f((bf16_t)raw[db][e]) * rinv * qg[db * 16 + hi * 8 + e];
;                 oa[e] = fa * cs - fb * sn; ob[e] = fb * cs + fa * sn; }
;             u32x4 wa = {cvt_pk_bf16(oa[0], oa[1]), cvt_pk_bf16(oa[2], oa[3]), cvt_pk_bf16(oa[4], oa[5]), cvt_pk_bf16(oa[6], oa[7])};
;             u32x4 wb = {cvt_pk_bf16(ob[0], ob[1]), cvt_pk_bf16(ob[2], ob[3]), cvt_pk_bf16(ob[4], ob[5]), cvt_pk_bf16(ob[6], ob[7])};
;             if constexpr (FIXED) { const u32x2 fa = pack8_fp8((f32x4){oa[0], oa[1], oa[2], oa[3]}, (f32x4){oa[4], oa[5], oa[6], oa[7]}), fb = pack8_fp8((f32x4){ob[0], ob[1], ob[2], ob[3]}, (f32x4){ob[4], ob[5], ob[6], ob[7]});
;                 q8[da >> 2][2 * (da & 3)] = (int)fa.x; q8[da >> 2][2 * (da & 3) + 1] = (int)fa.y; q8[db >> 2][2 * (db & 3)] = (int)fb.x; q8[db >> 2][2 * (db & 3) + 1] = (int)fb.y; }
;             else { qr[da] = *reinterpret_cast<bf16x8*>(&wa); qr[db] = *reinterpret_cast<bf16x8*>(&wb); }
;             asm volatile("" ::: "memory"); }
	v_mov_b32_e32 v126, v70
	s_waitcnt vmcnt(1)
	v_mov_b32_e32 v127, v78
	v_pk_mul_f32 v[26:27], v[26:27], v[126:127]
	v_mov_b32_e32 v78, v71
	v_pk_mul_f32 v[62:63], v[62:63], v[26:27]
	v_pk_mul_f32 v[26:27], v[98:99], v[26:27]
	v_sub_f32_e32 v59, v62, v63
	v_add_f32_e32 v125, v26, v27
	v_pk_mul_f32 v[26:27], v[10:11], v[28:29] op_sel_hi:[0,1]
	v_pk_mul_f32 v[26:27], v[26:27], v[78:79]
	v_cvt_pk_fp8_f32 v153, v55, v3 op_sel:[0,0,1]
	v_pk_mul_f32 v[28:29], v[74:75], v[26:27]
	v_pk_mul_f32 v[26:27], v[100:101], v[26:27]
	v_sub_f32_e32 v126, v28, v29
	v_add_f32_e32 v100, v26, v27
	v_pk_mul_f32 v[26:27], v[10:11], v[30:31] op_sel_hi:[0,1]
	v_mov_b32_e32 v28, v72
	v_mov_b32_e32 v29, v80
	v_pk_mul_f32 v[26:27], v[26:27], v[28:29]
	v_mov_b32_e32 v80, v73
	v_pk_mul_f32 v[28:29], v[86:87], v[26:27]
	v_pk_mul_f32 v[26:27], v[102:103], v[26:27]
	v_sub_f32_e32 v101, v28, v29
	v_add_f32_e32 v102, v26, v27
	v_pk_mul_f32 v[26:27], v[10:11], v[38:39] op_sel_hi:[0,1]
	v_pk_mul_f32 v[26:27], v[26:27], v[80:81]
	v_and_b32_e32 v30, 63, v115
	v_pk_mul_f32 v[28:29], v[88:89], v[26:27]
	v_pk_mul_f32 v[26:27], v[104:105], v[26:27]
	v_sub_f32_e32 v103, v28, v29
	v_add_f32_e32 v104, v26, v27
	v_pk_mul_f32 v[26:27], v[10:11], v[46:47] op_sel_hi:[0,1]
	v_mov_b32_e32 v28, v66
	s_waitcnt vmcnt(0)
	v_mov_b32_e32 v29, v82
	v_pk_mul_f32 v[26:27], v[26:27], v[28:29]
	v_mov_b32_e32 v82, v67
	v_pk_mul_f32 v[28:29], v[90:91], v[26:27]
	v_pk_mul_f32 v[26:27], v[106:107], v[26:27]
	v_sub_f32_e32 v105, v28, v29
	v_add_f32_e32 v106, v26, v27
	v_pk_mul_f32 v[26:27], v[10:11], v[56:57] op_sel_hi:[0,1]
	v_pk_mul_f32 v[26:27], v[26:27], v[82:83]
	v_cvt_pk_fp8_f32 v157, v0, v2 op_sel:[0,0,1]
	v_pk_mul_f32 v[28:29], v[92:93], v[26:27]
	v_pk_mul_f32 v[26:27], v[108:109], v[26:27]
	v_sub_f32_e32 v107, v28, v29
	v_add_f32_e32 v108, v26, v27
	v_pk_mul_f32 v[26:27], v[10:11], v[64:65] op_sel_hi:[0,1]
	v_mov_b32_e32 v28, v68
	v_mov_b32_e32 v29, v84
	v_pk_mul_f32 v[26:27], v[26:27], v[28:29]
	v_mov_b32_e32 v84, v69
	v_pk_mul_f32 v[28:29], v[94:95], v[26:27]
	v_pk_mul_f32 v[26:27], v[110:111], v[26:27]
	v_sub_f32_e32 v109, v28, v29
	v_add_f32_e32 v110, v26, v27
	v_pk_mul_f32 v[26:27], v[10:11], v[76:77] op_sel_hi:[0,1]
	v_pk_mul_f32 v[26:27], v[26:27], v[84:85]
	v_and_b32_e32 v2, 4, v195
	v_pk_mul_f32 v[28:29], v[96:97], v[26:27]
	v_pk_mul_f32 v[26:27], v[112:113], v[26:27]
	v_sub_f32_e32 v111, v28, v29
	v_add_f32_e32 v112, v26, v27
	v_cvt_pk_bf16_f32 v26, v59, v126
	v_cvt_f32_ubyte0_e32 v113, v30
	v_cvt_pk_bf16_f32 v26, v101, v103
	v_mul_f32_e32 v30, v119, v113
	v_cvt_pk_bf16_f32 v26, v105, v107
	v_mul_f32_e32 v31, 0.15915494, v30
	v_cvt_pk_bf16_f32 v26, v109, v111
	v_cos_f32_e32 v30, v31
	v_cvt_pk_bf16_f32 v26, v125, v100
	v_sin_f32_e32 v31, v31
	v_cvt_pk_bf16_f32 v26, v102, v104
	v_mul_f32_e32 v38, v120, v113
	v_cvt_pk_bf16_f32 v26, v106, v108
	v_mul_f32_e32 v39, 0.15915494, v38
	v_cvt_pk_bf16_f32 v26, v110, v112
	v_mov_b64_e32 v[26:27], v[224:225]
	v_mov_b64_e32 v[28:29], v[226:227]
	v_mov_b64_e32 v[62:63], v[228:229]
	v_mov_b64_e32 v[64:65], v[230:231]
	v_mov_b64_e32 v[66:67], v[232:233]
	v_mov_b64_e32 v[68:69], v[234:235]
	v_mov_b64_e32 v[70:71], v[236:237]
	v_mov_b64_e32 v[72:73], v[238:239]
	v_cos_f32_e32 v38, v39
	v_sin_f32_e32 v39, v39
	v_mul_f32_e32 v46, v118, v113
	v_mov_b32_e32 v82, v31
	v_mov_b32_e32 v83, v30
	v_mul_f32_e32 v47, 0.15915494, v46
	v_cos_f32_e32 v46, v47
	v_sin_f32_e32 v47, v47
	v_mul_f32_e32 v56, v117, v113
	v_mov_b32_e32 v84, v39
	v_mov_b32_e32 v85, v38
	v_mul_f32_e32 v57, 0.15915494, v56
	v_cos_f32_e32 v56, v57
	v_sin_f32_e32 v57, v57
	v_mul_f32_e32 v74, v116, v113
	v_mov_b32_e32 v86, v47
	v_mov_b32_e32 v87, v46
	v_mul_f32_e32 v75, 0.15915494, v74
	v_cos_f32_e32 v74, v75
	v_sin_f32_e32 v75, v75
	v_mul_f32_e32 v76, v121, v113
	v_mov_b32_e32 v88, v57
	v_mov_b32_e32 v89, v56
	v_mul_f32_e32 v77, 0.15915494, v76
	v_cos_f32_e32 v76, v77
	v_sin_f32_e32 v77, v77
	v_mul_f32_e32 v78, v122, v113
	v_mov_b32_e32 v90, v75
	v_mov_b32_e32 v91, v74
	v_mul_f32_e32 v79, 0.15915494, v78
	v_cos_f32_e32 v78, v79
	v_sin_f32_e32 v79, v79
	v_mul_f32_e32 v80, v124, v113
	v_mov_b32_e32 v92, v77
	v_mov_b32_e32 v93, v76
	v_mul_f32_e32 v81, 0.15915494, v80
	v_cos_f32_e32 v80, v81
	v_sin_f32_e32 v81, v81
	v_mov_b32_e32 v94, v79
	v_mov_b32_e32 v95, v78
	v_mov_b32_e32 v97, v80
	v_mov_b32_e32 v96, v81
	v_lshrrev_b32_e32 v3, 1, v195
	v_and_or_b32 v2, v3, 1, v2
	v_cvt_pk_fp8_f32 v156, v11, v4
	v_lshlrev_b32_e32 v0, 3, v195
	v_lshlrev_b32_e32 v2, 4, v2
	v_and_b32_e32 v4, 0x70, v195
	v_and_b32_e32 v0, 8, v0
	v_mov_b32_e32 v152, v179
	v_mov_b32_e32 v154, v179
	v_mov_b32_e32 v155, v179
	v_mov_b32_e32 v158, v179
	v_mov_b32_e32 v159, v179
	v_cvt_pk_fp8_f32 v152, v58, v5
	v_cvt_pk_fp8_f32 v154, v59, v126
	v_cvt_pk_fp8_f32 v155, v105, v107
	v_cvt_pk_fp8_f32 v158, v125, v100
	v_cvt_pk_fp8_f32 v159, v106, v108
	v_mov_b32_e32 v144, v179
	v_mov_b32_e32 v148, v179
	v_cvt_pk_fp8_f32 v152, v50, v6 op_sel:[0,0,1]
	v_cvt_pk_fp8_f32 v156, v51, v7 op_sel:[0,0,1]
	v_cvt_pk_fp8_f32 v154, v101, v103 op_sel:[0,0,1]
	v_cvt_pk_fp8_f32 v155, v109, v111 op_sel:[0,0,1]
	v_cvt_pk_fp8_f32 v158, v102, v104 op_sel:[0,0,1]
	v_cvt_pk_fp8_f32 v159, v110, v112 op_sel:[0,0,1]
	v_mov_b32_e32 v145, v179
	v_mov_b32_e32 v149, v179
	s_lshl_b64 s[44:45], s[44:45], 13
	v_mul_u32_u24_e32 v197, 0x50, v192
	s_mov_b32 s35, 1
	s_mov_b32 s3, 4
	v_and_b32_e32 v196, 63, v195
	v_add3_u32 v207, 0, v197, v193
	v_readlane_b32 s73, v254, 20
	s_waitcnt vmcnt(3)
	v_mov_b32_e32 v98, v26
	s_waitcnt vmcnt(2)
; __device__ __forceinline__ unsigned cvt_pk_bf16(float lo, float hi) { unsigned r; asm volatile("v_cvt_pk_bf16_f32 %0, %1, %2" : "=v"(r) : "v"(lo), "v"(hi)); return r; }
; __device__ __forceinline__ float bf2f(bf16_t v) { return __uint_as_float((unsigned)v << 16); }
; __device__ __forceinline__ float fast_exp2(float x) { return __builtin_amdgcn_exp2f(x); }
; template <bool FIXED> ...
;     ...
;         for (int pr = 0; pr < 4; ++pr) { const int da = (pr & 1) + ((pr >> 1) << 2), db = da + 2; const float pos = (pr >> 1) ? pcol : prow; float oa[8], ob[8];
; #pragma unroll
;             for (int e = 0; e < 8; ++e) { const int i = (da & 1) * 16 + hi * 8 + e; const float rev = pos * fast_exp2(-(float)i * ROPE_L2) * INV2PI;
;                 const float cs = __builtin_amdgcn_cosf(rev), sn = __builtin_amdgcn_sinf(rev);
;                 const float fa = bf2f((bf16_t)raw[da][e]) * rinv * qg[da * 16 + hi * 8 + e], fb = bf2f((bf16_t)raw[db][e]) * rinv * qg[db * 16 + hi * 8 + e];
;                 oa[e] = fa * cs - fb * sn; ob[e] = fb * cs + fa * sn; }
;             u32x4 wa = {cvt_pk_bf16(oa[0], oa[1]), cvt_pk_bf16(oa[2], oa[3]), cvt_pk_bf16(oa[4], oa[5]), cvt_pk_bf16(oa[6], oa[7])};
;             u32x4 wb = {cvt_pk_bf16(ob[0], ob[1]), cvt_pk_bf16(ob[2], ob[3]), cvt_pk_bf16(ob[4], ob[5]), cvt_pk_bf16(ob[6], ob[7])};
;             if constexpr (FIXED) { const u32x2 fa = pack8_fp8((f32x4){oa[0], oa[1], oa[2], oa[3]}, (f32x4){oa[4], oa[5], oa[6], oa[7]}), fb = pack8_fp8((f32x4){ob[0], ob[1], ob[2], ob[3]}, (f32x4){ob[4], ob[5], ob[6], ob[7]});
;                 q8[da >> 2][2 * (da & 3)] = (int)fa.x; q8[da >> 2][2 * (da & 3) + 1] = (int)fa.y; q8[db >> 2][2 * (db & 3)] = (int)fb.x; q8[db >> 2][2 * (db & 3) + 1] = (int)fb.y; }
;             else { qr[da] = *reinterpret_cast<bf16x8*>(&wa); qr[db] = *reinterpret_cast<bf16x8*>(&wb); }
;             asm volatile("" ::: "memory"); }
	v_mov_b32_e32 v99, v62
	v_pk_mul_f32 v[32:33], v[32:33], v[98:99]
	v_mov_b32_e32 v62, v27
	v_pk_mul_f32 v[30:31], v[30:31], v[32:33]
	v_readlane_b32 s74, v254, 21
	v_sub_f32_e32 v98, v30, v31
	v_pk_mul_f32 v[30:31], v[82:83], v[32:33]
	v_readlane_b32 s75, v254, 22
	v_add_f32_e32 v82, v30, v31
	v_pk_mul_f32 v[30:31], v[10:11], v[34:35] op_sel_hi:[0,1]
	v_pk_mul_f32 v[26:27], v[30:31], v[62:63]
	v_mul_f32_e32 v62, v134, v113
	v_pk_mul_f32 v[30:31], v[38:39], v[26:27]
	v_pk_mul_f32 v[26:27], v[84:85], v[26:27]
	v_sub_f32_e32 v83, v30, v31
	v_add_f32_e32 v84, v26, v27
	v_pk_mul_f32 v[26:27], v[10:11], v[36:37] op_sel_hi:[0,1]
	v_mov_b32_e32 v30, v28
	v_mov_b32_e32 v31, v64
	v_pk_mul_f32 v[26:27], v[26:27], v[30:31]
	v_mov_b32_e32 v64, v29
	v_pk_mul_f32 v[30:31], v[46:47], v[26:27]
	v_pk_mul_f32 v[26:27], v[86:87], v[26:27]
	v_sub_f32_e32 v85, v30, v31
	v_add_f32_e32 v86, v26, v27
	v_pk_mul_f32 v[26:27], v[10:11], v[40:41] op_sel_hi:[0,1]
	v_pk_mul_f32 v[26:27], v[26:27], v[64:65]
	v_mul_f32_e32 v46, v129, v113
	v_pk_mul_f32 v[28:29], v[56:57], v[26:27]
	v_pk_mul_f32 v[26:27], v[88:89], v[26:27]
	v_sub_f32_e32 v87, v28, v29
	v_add_f32_e32 v88, v26, v27
	v_pk_mul_f32 v[26:27], v[10:11], v[44:45] op_sel_hi:[0,1]
	s_waitcnt vmcnt(1)
	v_mov_b32_e32 v28, v66
	s_waitcnt vmcnt(0)
	v_mov_b32_e32 v29, v70
	v_pk_mul_f32 v[26:27], v[26:27], v[28:29]
	v_mov_b32_e32 v70, v67
	v_pk_mul_f32 v[28:29], v[74:75], v[26:27]
	v_pk_mul_f32 v[26:27], v[90:91], v[26:27]
	v_sub_f32_e32 v74, v28, v29
	v_add_f32_e32 v75, v26, v27
	v_pk_mul_f32 v[26:27], v[10:11], v[48:49] op_sel_hi:[0,1]
	v_pk_mul_f32 v[26:27], v[26:27], v[70:71]
	v_mul_f32_e32 v44, v128, v113
	v_pk_mul_f32 v[28:29], v[76:77], v[26:27]
	v_pk_mul_f32 v[26:27], v[92:93], v[26:27]
	v_sub_f32_e32 v70, v28, v29
	v_add_f32_e32 v71, v26, v27
	v_pk_mul_f32 v[26:27], v[10:11], v[52:53] op_sel_hi:[0,1]
	v_mov_b32_e32 v28, v68
	v_mov_b32_e32 v29, v72
	v_pk_mul_f32 v[26:27], v[26:27], v[28:29]
	v_mov_b32_e32 v72, v69
	v_pk_mul_f32 v[28:29], v[78:79], v[26:27]
	v_pk_mul_f32 v[26:27], v[94:95], v[26:27]
	v_sub_f32_e32 v68, v28, v29
	v_add_f32_e32 v76, v26, v27
	v_pk_mul_f32 v[26:27], v[10:11], v[60:61] op_sel_hi:[0,1]
	v_pk_mul_f32 v[26:27], v[26:27], v[72:73]
	v_mul_f32_e32 v45, 0.15915494, v44
	v_pk_mul_f32 v[28:29], v[80:81], v[26:27]
	v_pk_mul_f32 v[26:27], v[96:97], v[26:27]
	v_sub_f32_e32 v69, v28, v29
	v_add_f32_e32 v72, v26, v27
	v_cvt_pk_bf16_f32 v26, v98, v83
	v_cos_f32_e32 v44, v45
	v_cvt_pk_bf16_f32 v26, v85, v87
	v_sin_f32_e32 v45, v45
	v_cvt_pk_bf16_f32 v26, v74, v70
	v_mul_f32_e32 v47, 0.15915494, v46
	v_cvt_pk_bf16_f32 v26, v68, v69
	v_cos_f32_e32 v46, v47
	v_cvt_pk_bf16_f32 v26, v82, v84
	v_sin_f32_e32 v47, v47
	v_cvt_pk_bf16_f32 v26, v86, v88
	v_mul_f32_e32 v48, v130, v113
	v_cvt_pk_bf16_f32 v26, v75, v71
	v_mul_f32_e32 v49, 0.15915494, v48
	v_cvt_pk_bf16_f32 v26, v76, v72
	v_mov_b64_e32 v[26:27], v[240:241]
	v_mov_b64_e32 v[28:29], v[242:243]
	v_mov_b64_e32 v[30:31], v[244:245]
	v_mov_b64_e32 v[32:33], v[246:247]
	v_mov_b64_e32 v[34:35], v[248:249]
	v_mov_b64_e32 v[36:37], v[250:251]
	v_mov_b64_e32 v[38:39], v[184:185]
	v_mov_b64_e32 v[40:41], v[186:187]
	v_cos_f32_e32 v48, v49
	v_sin_f32_e32 v49, v49
	v_mul_f32_e32 v52, v131, v113
	v_mul_f32_e32 v53, 0.15915494, v52
	v_cos_f32_e32 v52, v53
	v_sin_f32_e32 v53, v53
	v_mul_f32_e32 v56, v132, v113
	v_mul_f32_e32 v57, 0.15915494, v56
	v_cos_f32_e32 v56, v57
	v_sin_f32_e32 v57, v57
	v_mul_f32_e32 v60, v133, v113
	v_mul_f32_e32 v61, 0.15915494, v60
	v_cos_f32_e32 v60, v61
	v_sin_f32_e32 v61, v61
	v_mul_f32_e32 v63, 0.15915494, v62
	v_cos_f32_e32 v62, v63
	v_sin_f32_e32 v63, v63
	v_mul_f32_e32 v64, v123, v113
	v_mul_f32_e32 v65, 0.15915494, v64
	v_cos_f32_e32 v64, v65
	v_sin_f32_e32 v65, v65
	v_cvt_pk_fp8_f32 v144, v98, v83
	v_cvt_pk_fp8_f32 v148, v82, v84
	v_cvt_pk_fp8_f32 v145, v74, v70
	v_cvt_pk_fp8_f32 v149, v75, v71
	v_cvt_pk_fp8_f32 v144, v85, v87 op_sel:[0,0,1]
	v_cvt_pk_fp8_f32 v148, v86, v88 op_sel:[0,0,1]
	v_cvt_pk_fp8_f32 v145, v68, v69 op_sel:[0,0,1]
	v_cvt_pk_fp8_f32 v149, v76, v72 op_sel:[0,0,1]
	v_readlane_b32 s76, v254, 23
	v_readlane_b32 s77, v254, 24
	v_readlane_b32 s78, v254, 25
	v_readlane_b32 s79, v254, 26
	v_readlane_b32 s80, v254, 27
	v_readlane_b32 s81, v254, 28
	v_readlane_b32 s84, v254, 31
	v_readlane_b32 s85, v254, 32
	v_readlane_b32 s86, v254, 33
	v_readlane_b32 s87, v254, 34
	s_waitcnt vmcnt(3)
	v_mov_b32_e32 v66, v26
	s_waitcnt vmcnt(2)
	v_mov_b32_e32 v67, v30
	v_pk_mul_f32 v[20:21], v[20:21], v[66:67]
	v_mov_b32_e32 v30, v27
	v_pk_mul_f32 v[66:67], v[44:45], v[20:21]
	v_pk_mul_f32 v[16:17], v[16:17], v[30:31]
	v_sub_f32_e32 v26, v66, v67
	v_mov_b32_e32 v66, v45
	v_mov_b32_e32 v67, v44
	v_pk_mul_f32 v[20:21], v[66:67], v[20:21]
	s_nop 0
	v_add_f32_e32 v44, v20, v21
	v_pk_mul_f32 v[20:21], v[46:47], v[16:17]
	s_nop 0
	v_sub_f32_e32 v27, v20, v21
	v_mov_b32_e32 v20, v47
	v_mov_b32_e32 v21, v46
	v_pk_mul_f32 v[16:17], v[20:21], v[16:17]
	v_cvt_pk_fp8_f32 v146, v26, v27
	v_add_f32_e32 v20, v16, v17
	v_pk_mul_f32 v[16:17], v[10:11], v[18:19] op_sel_hi:[0,1]
	v_mov_b32_e32 v18, v28
	v_mov_b32_e32 v19, v32
	v_pk_mul_f32 v[16:17], v[16:17], v[18:19]
	v_mov_b32_e32 v32, v29
	v_pk_mul_f32 v[18:19], v[48:49], v[16:17]
	v_pk_mul_f32 v[12:13], v[12:13], v[32:33]
	v_sub_f32_e32 v21, v18, v19
	v_mov_b32_e32 v18, v49
	v_mov_b32_e32 v19, v48
	v_pk_mul_f32 v[16:17], v[18:19], v[16:17]
	v_lshlrev_b32_e32 v32, 4, v195
	v_add_f32_e32 v28, v16, v17
	v_pk_mul_f32 v[16:17], v[52:53], v[12:13]
	v_ashrrev_i32_e32 v33, 31, v32
	v_sub_f32_e32 v29, v16, v17
	v_mov_b32_e32 v16, v53
	v_mov_b32_e32 v17, v52
	v_pk_mul_f32 v[12:13], v[16:17], v[12:13]
	v_and_b32_e32 v178, 0x70, v32
	v_add_f32_e32 v30, v12, v13
	s_waitcnt vmcnt(1)
; #define MFMA_DRAIN2(a, b) asm volatile("s_nop 15\n s_nop 15\n s_nop 15\n s_nop 15\n s_nop 15" : "+v"(a), "+v"(b))
; __device__ __forceinline__ int v_st(int k, int c) { const int kk = (k & ~0xC) | ((k & 4) << 1) | ((k & 8) >> 1); return ((kk >> 3) * 4 + (c >> 5)) * 512 + ((kk & 7) * 32 + (c & 31)) * 2; }
; __device__ __forceinline__ int v_rd_base(int lane) { return ((lane & 3) << 3) | (((lane >> 2) & 3) << 6) | (((lane >> 4) & 1) << 5) | (((lane >> 5) & 1) << 8); }
; #define SWAIT() do { if constexpr (FIXED) asm volatile("s_waitcnt vmcnt(2)" ::: "memory"); else if constexpr (SD == 2) asm volatile("s_waitcnt vmcnt(4)" ::: "memory"); else asm volatile("s_waitcnt vmcnt(0)" ::: "memory"); } while (0)
; #define PSM(P0, P1, MN, AL) do { if constexpr (FIXED) partialSM_fixed(P0); else partialSM(P0, P1, m_reg, MN, AL); } while (0)
; #define QKT(P0, P1, KP) do { if constexpr (FIXED) qkt8(P0, P1, KP, q8, r32, hi); else qkt<false>(P0, P1, (const bf16_t*)(KP), qr, r32, hi, qinit); } while (0)
; template <bool FIXED> ...
;     ...
;     const int sr = tid >> 4, sc = (tid & 15) * 8, vst0 = v_st(sr, sc), vst1 = v_st(32 + sr, sc);
;     const int vb0 = (int)(uintptr_t)V_lds + v_rd_base(lane);
;     constexpr int SD = FIXED ? 2 : 1;
;     struct { bf16x8 vs0, vs1, ks0, ks1; } sr_[SD];
;     const int k8key = tid >> 3, k8gg = tid & 7, k8off = k8key * 128 + (((4 * (k8gg >> 2) + ((k8gg & 3) >> 1)) ^ ((k8key >> 1) & 7)) * 16) + (k8gg & 1) * 8;
;     ...
;     f32x16 pA0, pA1, pB0, pB1; float mnA, mnB, alA, alB; if constexpr (FIXED) { mnA = mnB = 0.f; alA = alB = 1.f; } bf16x8 pa0, pa1, pa2, pa3; const int NT = seq / KVBLK;
;     const float qinit = 0.f;
;     i32x8 pa8;
;     ...
;     constexpr int SE = 0, SO = SD - 1;
;     SLOAD(SE, 0); asm volatile("s_waitcnt vmcnt(0)" ::: "memory"); SWRITE(0, SE); __syncthreads();
;     QKT(pA0, pA1, (const char*)K_lds); if constexpr (FIXED) MFMA_DRAIN2(pA0, pA1); PSM(pA0, pA1, mnA, alA);
;     SLOAD(SO, KVBLK); if constexpr (SD == 2) { if (2 < NT) SLOAD(SE, 2 * KVBLK); }
;     SWAIT(); SWRITE(1, SO); __syncthreads();
	v_mov_b32_e32 v12, v34
	s_waitcnt vmcnt(0)
	v_mov_b32_e32 v13, v38
	v_pk_mul_f32 v[8:9], v[8:9], v[12:13]
	v_mov_b32_e32 v38, v35
	v_pk_mul_f32 v[12:13], v[56:57], v[8:9]
	v_lshl_add_u64 v[34:35], s[46:47], 0, v[32:33]
	v_sub_f32_e32 v31, v12, v13
	v_mov_b32_e32 v12, v57
	v_mov_b32_e32 v13, v56
	v_pk_mul_f32 v[8:9], v[12:13], v[8:9]
	v_cvt_pk_fp8_f32 v150, v44, v20
	v_add_f32_e32 v45, v8, v9
	v_pk_mul_f32 v[8:9], v[10:11], v[22:23] op_sel_hi:[0,1]
	v_pk_mul_f32 v[8:9], v[8:9], v[38:39]
	v_cvt_pk_fp8_f32 v146, v21, v29 op_sel:[0,0,1]
	v_pk_mul_f32 v[12:13], v[60:61], v[8:9]
	v_cvt_pk_fp8_f32 v150, v28, v30 op_sel:[0,0,1]
	v_sub_f32_e32 v22, v12, v13
	v_mov_b32_e32 v12, v61
	v_mov_b32_e32 v13, v60
	v_pk_mul_f32 v[8:9], v[12:13], v[8:9]
	v_mov_b32_e32 v12, v36
	v_add_f32_e32 v23, v8, v9
	v_pk_mul_f32 v[8:9], v[10:11], v[24:25] op_sel_hi:[0,1]
	v_mov_b32_e32 v13, v40
	v_pk_mul_f32 v[8:9], v[8:9], v[12:13]
	v_mov_b32_e32 v40, v37
	v_pk_mul_f32 v[12:13], v[62:63], v[8:9]
	v_cvt_pk_fp8_f32 v147, v31, v22
	v_sub_f32_e32 v24, v12, v13
	v_mov_b32_e32 v12, v63
	v_mov_b32_e32 v13, v62
	v_pk_mul_f32 v[8:9], v[12:13], v[8:9]
	v_cvt_pk_fp8_f32 v151, v45, v23
	v_add_f32_e32 v46, v8, v9
	v_pk_mul_f32 v[8:9], v[10:11], v[14:15] op_sel_hi:[0,1]
	v_pk_mul_f32 v[8:9], v[8:9], v[40:41]
	v_lshlrev_b32_e32 v41, 1, v114
	v_pk_mul_f32 v[12:13], v[64:65], v[8:9]
	s_and_b32 s47, s48, 0xffff8000
	v_sub_f32_e32 v10, v12, v13
	v_mov_b32_e32 v12, v65
	v_mov_b32_e32 v13, v64
	v_pk_mul_f32 v[8:9], v[12:13], v[8:9]
	v_cvt_pk_fp8_f32 v147, v24, v10 op_sel:[0,0,1]
	v_add_f32_e32 v40, v8, v9
	v_cvt_pk_bf16_f32 v8, v26, v27
	v_cvt_pk_fp8_f32 v151, v46, v40 op_sel:[0,0,1]
	v_cvt_pk_bf16_f32 v8, v21, v29
	s_add_u32 s44, s47, s44
	v_cvt_pk_bf16_f32 v8, v31, v22
	s_addc_u32 s45, s49, s45
	v_cvt_pk_bf16_f32 v8, v24, v10
	s_mov_b32 s46, 2
	v_cvt_pk_bf16_f32 v8, v44, v20
	v_lshl_add_u64 v[182:183], s[44:45], 0, v[32:33]
	v_cvt_pk_bf16_f32 v8, v28, v30
	s_mov_b32 s44, 0
	v_cvt_pk_bf16_f32 v8, v45, v23
	v_mov_b32_e32 v48, 0
	v_cvt_pk_bf16_f32 v8, v46, v40
	v_ashrrev_i32_e32 v8, 3, v195
	v_ashrrev_i32_e32 v9, 31, v8
	v_lshlrev_b64 v[36:37], 9, v[8:9]
	v_lshl_add_u64 v[16:17], s[52:53], 0, v[36:37]
	v_lshl_add_u64 v[38:39], v[16:17], 0, v[178:179]
	v_lshlrev_b32_e32 v1, 7, v8
	v_bitop3_b32 v1, v2, v1, v4 bitop3:0xde
	v_lshrrev_b32_e32 v2, 2, v195
	v_or_b32_e32 v198, v1, v0
	v_mul_lo_u32 v2, v2, s56
	v_and_b32_e32 v4, 48, v32
	v_bitop3_b32 v200, v1, 32, v0 bitop3:0x36
	v_add3_u32 v199, 0, v2, v4
	v_add_u32_e32 v2, 0, v198
	v_add_u32_e32 v0, 0, v200
	s_waitcnt vmcnt(0)
	v_bfe_u32 v40, v195, 1, 3
	v_mov_b32_e32 v32, 0
	s_waitcnt vmcnt(1)
	ds_write_b128 v199, v[136:139]
	s_waitcnt vmcnt(0)
	ds_write_b64 v2, v[140:141] offset:49152
	ds_write_b64 v0, v[142:143] offset:49152
	v_bitop3_b32 v0, v41, v3, 7 bitop3:0x78
	v_lshlrev_b32_e32 v202, 4, v0
	v_add_u32_e32 v0, v204, v202
	v_xor_b32_e32 v203, 16, v202
	s_waitcnt lgkmcnt(0)
	s_barrier
	v_add_u32_e32 v1, v204, v203
	ds_read_b128 v[16:19], v0 offset:49152
	ds_read_b128 v[24:27], v0 offset:53248
	ds_read_b128 v[20:23], v1 offset:49152
	ds_read_b128 v[28:31], v1 offset:53248
	s_waitcnt lgkmcnt(0)
	s_waitcnt lgkmcnt(1)
	v_mfma_scale_f32_32x32x64_f8f6f4 v[0:15], v[16:23], v[152:159], -4.0, v189, v190 op_sel_hi:[0,0,0]
	v_bitop3_b32 v16, v41, v40, 4 bitop3:0x36
	v_lshlrev_b32_e32 v205, 4, v16
	v_xor_b32_e32 v206, 16, v205
	s_waitcnt lgkmcnt(0)
	v_mfma_scale_f32_32x32x64_f8f6f4 v[80:95], v[24:31], v[152:159], -4.0, v189, v190 op_sel_hi:[0,0,0]
	v_add_u32_e32 v20, v204, v205
	v_add_u32_e32 v28, v204, v206
	ds_read_b128 v[16:19], v20 offset:49152
	ds_read_b128 v[24:27], v20 offset:53248
	ds_read_b128 v[20:23], v28 offset:49152
	ds_read_b128 v[28:31], v28 offset:53248
	s_waitcnt lgkmcnt(0)
	s_waitcnt lgkmcnt(1)
	v_mfma_scale_f32_32x32x64_f8f6f4 v[0:15], v[16:23], v[144:151], v[0:15], v189, v190 op_sel_hi:[0,0,0]
	v_add_co_u32_e32 v16, vcc, s57, v34
	s_waitcnt lgkmcnt(0)
	v_mfma_scale_f32_32x32x64_f8f6f4 v[80:95], v[24:31], v[144:151], v[80:95], v189, v190 op_sel_hi:[0,0,0]
	s_nop 0
	v_addc_co_u32_e32 v17, vcc, 0, v35, vcc
	v_add_co_u32_e32 v20, vcc, s57, v38
	s_nop 15
 s_nop 15
 s_nop 15
 s_nop 15
 s_nop 15
	s_nop 0
	v_addc_co_u32_e32 v21, vcc, 0, v39, vcc
	v_add_co_u32_e32 v24, vcc, s60, v38
	s_nop 0
	v_addc_co_u32_e32 v25, vcc, 0, v39, vcc
	v_add_co_u32_e32 v26, vcc, s60, v34
	v_exp_f32_e32 v64, v0
	s_nop 0
	v_addc_co_u32_e32 v27, vcc, 0, v35, vcc
	global_load_dwordx4 v[160:163], v[24:25], off
	global_load_dwordx4 v[164:167], v[26:27], off
	v_exp_f32_e32 v65, v1
	v_exp_f32_e32 v66, v2
	v_exp_f32_e32 v67, v3
	v_exp_f32_e32 v68, v4
	v_exp_f32_e32 v69, v5
	v_exp_f32_e32 v70, v6
	v_exp_f32_e32 v71, v7
	v_exp_f32_e32 v72, v8
	v_exp_f32_e32 v73, v9
	v_exp_f32_e32 v74, v10
	v_exp_f32_e32 v75, v11
	v_exp_f32_e32 v76, v12
	v_exp_f32_e32 v77, v13
	v_exp_f32_e32 v78, v14
	v_exp_f32_e32 v79, v15
	s_waitcnt vmcnt(2)
	v_lshl_add_u64 v[0:1], s[48:49], 0, v[36:37]
	v_or_b32_e32 v0, v0, v178
	v_mov_b32_e32 v178, 0
	v_lshl_add_u64 v[180:181], v[0:1], 0, s[50:51]
	v_mov_b32_e32 v0, 0
	v_mov_b32_e32 v1, v178
	v_mov_b32_e32 v2, v178
	v_mov_b32_e32 v3, v178
	v_mov_b32_e32 v4, v178
	v_mov_b32_e32 v5, v178
	v_mov_b32_e32 v6, v178
	v_mov_b32_e32 v7, v178
	v_mov_b32_e32 v8, v178
	v_mov_b32_e32 v9, v178
	v_mov_b32_e32 v10, v178
	v_mov_b32_e32 v11, v178
	v_mov_b32_e32 v12, v178
	v_mov_b32_e32 v13, v178
	v_mov_b32_e32 v14, v178
	v_mov_b32_e32 v15, v178
	v_mov_b32_e32 v24, v178
	v_mov_b32_e32 v25, v178
	v_mov_b32_e32 v26, v178
	v_mov_b32_e32 v27, v178
	v_mov_b32_e32 v28, v178
	v_mov_b32_e32 v29, v178
	v_mov_b32_e32 v30, v178
	v_mov_b32_e32 v31, v178
	v_mov_b32_e32 v33, v178
	v_mov_b32_e32 v34, v178
	v_mov_b32_e32 v35, v178
	v_mov_b32_e32 v36, v178
	v_mov_b32_e32 v37, v178
	v_mov_b32_e32 v38, v178
	v_mov_b32_e32 v39, v178
	v_mov_b32_e32 v40, v178
	v_mov_b32_e32 v41, v178
	v_mov_b32_e32 v42, v178
	v_mov_b32_e32 v43, v178
	v_mov_b32_e32 v44, v178
	v_mov_b32_e32 v45, v178
	v_mov_b32_e32 v46, v178
	v_mov_b32_e32 v47, v178
	v_mov_b32_e32 v49, v178
	v_mov_b32_e32 v50, v178
	v_mov_b32_e32 v51, v178
	v_mov_b32_e32 v52, v178
	v_mov_b32_e32 v53, v178
	v_mov_b32_e32 v54, v178
	v_mov_b32_e32 v55, v178
	s_waitcnt vmcnt(3)
	ds_write_b128 v199, v[168:171] offset:16384
	v_add_u32_e32 v16, s61, v198
	v_mov_b32_e32 v17, v178
	v_mov_b32_e32 v18, v178
	v_mov_b32_e32 v19, v178
	s_waitcnt vmcnt(2)
	ds_write_b64 v16, v[172:173]
	v_add_u32_e32 v16, s61, v200
	ds_write_b64 v16, v[174:175]
	v_mov_b32_e32 v16, 0
	v_mov_b32_e32 v20, v178
	v_mov_b32_e32 v21, v178
	v_mov_b32_e32 v22, v178
	v_mov_b32_e32 v23, v178
	v_mov_b32_e32 v56, v178
	v_mov_b32_e32 v57, v178
	v_mov_b32_e32 v58, v178
	v_mov_b32_e32 v59, v178
	v_mov_b32_e32 v60, v178
	v_mov_b32_e32 v61, v178
	v_mov_b32_e32 v62, v178
	v_mov_b32_e32 v63, v178
	s_waitcnt lgkmcnt(0)
	s_barrier
